# P4 attention gathered-tile loops: the no-mask path is a full renamed copy of the iteration that reads the scores where the MFMA left them (no 8 v_mov per iteration)
# baseline (speedup 1.0000x reference)
; DI unsigned pack2bf(float a, float b) { const f2_t v = {a, b}; return __builtin_bit_cast(unsigned, __builtin_convertvector(v, bf2_t)); }
; DI float xor32_max(float v) { const auto r = __builtin_amdgcn_permlane32_swap(__float_as_uint(v), __float_as_uint(v), false, false); return fmaxf(__uint_as_float(r[0]), __uint_as_float(r[1])); }
; DI void attn_task(const Params& P, int bh, int n, int t, int lane, const char* Ks, const char* Vs) {
;     ...
; #pragma unroll
;     for (int s = 0; s < 4; ++s) {
;       const bf16x8 kf = *reinterpret_cast<const bf16x8*>(Ks + krow * 128 + (((2 * s + hh) ^ ((krow >> 1) & 7)) * 16));
;       S = __builtin_amdgcn_mfma_f32_32x32x16_bf16(kf, qf[s], S, 0, 0, 0);
;     }
;     const bool diag = own && (kt == t);
;     constexpr float SC2 = 0.125f * 1.4426950408889634f;
;     float mx = -1e30f;
; #pragma unroll
;     for (int i = 0; i < 16; ++i) {
;       if (diag && (kbase + crow(i, hh) > lq)) S[i] = -1e30f;
;       mx = fmaxf(mx, S[i]);
;     }
;     mx = xor32_max(mx);
;     const float m_new = fmaxf(m_run, mx * SC2);
;     const float alpha = __builtin_amdgcn_exp2f(m_run - m_new);
;     float rs = 0.f;
; #pragma unroll
;     for (int i = 0; i < 16; ++i) { float pv = __builtin_amdgcn_exp2f(fmaf(S[i], SC2, -m_new)); S[i] = pv; rs += pv; }
;     rs = xor32_sum(rs);
;     l_run = l_run * alpha + rs; m_run = m_new;
;     if (__ballot(alpha != 1.f)) {
; #pragma unroll
;       for (int i = 0; i < 16; ++i) { O0[i] *= alpha; O1[i] *= alpha; }
;     }
; #pragma unroll
;     for (int s = 0; s < 2; ++s) {
;       const uint4 ppk = make_uint4(pack2bf(S[8 * s], S[8 * s + 1]), pack2bf(S[8 * s + 2], S[8 * s + 3]), pack2bf(S[8 * s + 4], S[8 * s + 5]), pack2bf(S[8 * s + 6], S[8 * s + 7]));
;       const bf16x8 pf = __builtin_bit_cast(bf16x8, ppk);
; #pragma unroll
;       for (int dt = 0; dt < 2; ++dt) {
;         const char* vp = Vs + (dt * 32 + r) * 528 + (kt * 32 + 16 * s + 4 * hh) * 2;
;         const uint2 lo = *reinterpret_cast<const uint2*>(vp), hi = *reinterpret_cast<const uint2*>(vp + 16);
;         const uint4 vv = make_uint4(lo.x, lo.y, hi.x, hi.y);
;         if (dt == 0) O0 = __builtin_amdgcn_mfma_f32_32x32x16_bf16(__builtin_bit_cast(bf16x8, vv), pf, O0, 0, 0, 0);
;         else O1 = __builtin_amdgcn_mfma_f32_32x32x16_bf16(__builtin_bit_cast(bf16x8, vv), pf, O1, 0, 0, 0);
;       }
;     }
.Lattn_fast_790:
	s_waitcnt vmcnt(3) lgkmcnt(2)
	v_mfma_f32_32x32x16_bf16 v[34:49], v[34:37], v[50:53], 0
	s_waitcnt vmcnt(2) lgkmcnt(1)
	v_mfma_f32_32x32x16_bf16 v[34:49], v[152:155], v[54:57], v[34:49]
	ds_read_b128 v[152:155], v160
	v_add_u32_e32 v210, v149, v197
	v_add_u32_e32 v211, v150, v197
	ds_read2_b64 v[216:219], v210 offset1:2
	ds_read2_b64 v[220:223], v211 offset1:2
	ds_read2_b64 v[224:227], v210 offset0:4 offset1:6
	ds_read2_b64 v[228:231], v211 offset0:4 offset1:6
	s_waitcnt vmcnt(1) lgkmcnt(5)
	v_mfma_f32_32x32x16_bf16 v[34:49], v[156:159], v[58:61], v[34:49]
	s_waitcnt vmcnt(0) lgkmcnt(4)
	v_mfma_f32_32x32x16_bf16 v[34:49], v[152:155], v[62:65], v[34:49]
	s_nop 11
	v_max3_f32 v176, v34, s22, v35
	v_max3_f32 v176, v176, v36, v37
	v_max3_f32 v176, v176, v38, v39
	v_max3_f32 v176, v176, v40, v41
	v_max3_f32 v176, v176, v42, v43
	v_max3_f32 v176, v176, v44, v45
	v_max3_f32 v176, v176, v46, v47
	v_max3_f32 v176, v176, v48, v49
	v_mov_b32_e32 v177, v176
	s_nop 1
	v_permlane32_swap_b32_e32 v176, v177
	v_max_f32_e32 v177, v177, v177
	v_max_f32_e32 v176, v176, v176
	v_max_f32_e32 v176, v176, v177
	v_mul_f32_e32 v176, 0x3e38aa3b, v176
	v_max_f32_e32 v177, v0, v0
	v_max_f32_e32 v71, v177, v176
	v_fma_f32 v34, v34, s23, -v71
	v_exp_f32_e32 v176, v34
	v_fma_f32 v34, v35, s23, -v71
	v_exp_f32_e32 v177, v34
	v_fma_f32 v34, v36, s23, -v71
	v_exp_f32_e32 v178, v34
	v_fma_f32 v34, v37, s23, -v71
	v_exp_f32_e32 v179, v34
	v_fma_f32 v37, v38, s23, -v71
	v_add_f32_e32 v34, 0, v176
	v_exp_f32_e32 v180, v37
	v_fma_f32 v37, v39, s23, -v71
	v_add_f32_e32 v34, v177, v34
	v_exp_f32_e32 v181, v37
	v_fma_f32 v37, v40, s23, -v71
	v_add_f32_e32 v34, v178, v34
	v_exp_f32_e32 v182, v37
	v_fma_f32 v37, v41, s23, -v71
	v_add_f32_e32 v34, v179, v34
	v_exp_f32_e32 v183, v37
	v_add_f32_e32 v34, v180, v34
	v_add_f32_e32 v34, v181, v34
	v_add_f32_e32 v34, v182, v34
	v_add_f32_e32 v152, v183, v34
	v_fma_f32 v34, v42, s23, -v71
	v_exp_f32_e32 v34, v34
	v_fma_f32 v37, v43, s23, -v71
	v_exp_f32_e32 v37, v37
	v_fma_f32 v38, v44, s23, -v71
	v_exp_f32_e32 v38, v38
	v_fma_f32 v40, v45, s23, -v71
	v_exp_f32_e32 v40, v40
	v_add_f32_e32 v42, v34, v152
	v_add_f32_e32 v42, v37, v42
	v_add_f32_e32 v42, v38, v42
	v_add_f32_e32 v152, v40, v42
	v_fma_f32 v42, v46, s23, -v71
	v_exp_f32_e32 v42, v42
	v_fma_f32 v44, v47, s23, -v71
	v_exp_f32_e32 v44, v44
	v_fma_f32 v46, v48, s23, -v71
	v_exp_f32_e32 v46, v46
	v_fma_f32 v48, v49, s23, -v71
	v_exp_f32_e32 v48, v48
	v_sub_f32_e32 v0, v0, v71
	v_add_f32_e32 v152, v42, v152
	v_add_f32_e32 v152, v44, v152
	v_exp_f32_e32 v0, v0
	v_add_f32_e32 v152, v46, v152
	v_add_f32_e32 v152, v48, v152
	v_mov_b32_e32 v153, v152
	s_nop 1
	v_permlane32_swap_b32_e32 v152, v153
	v_cmp_neq_f32_e32 vcc, 1.0, v0
	s_cbranch_vccz .Lattn_fx_skip_790
	v_pk_mul_f32 v[32:33], v[32:33], v[0:1] op_sel_hi:[1,0]
	v_pk_mul_f32 v[30:31], v[30:31], v[0:1] op_sel_hi:[1,0]
	v_pk_mul_f32 v[28:29], v[28:29], v[0:1] op_sel_hi:[1,0]
	v_pk_mul_f32 v[26:27], v[26:27], v[0:1] op_sel_hi:[1,0]
	v_pk_mul_f32 v[24:25], v[24:25], v[0:1] op_sel_hi:[1,0]
	v_pk_mul_f32 v[22:23], v[22:23], v[0:1] op_sel_hi:[1,0]
	v_pk_mul_f32 v[20:21], v[20:21], v[0:1] op_sel_hi:[1,0]
	v_pk_mul_f32 v[18:19], v[18:19], v[0:1] op_sel_hi:[1,0]
	v_pk_mul_f32 v[16:17], v[16:17], v[0:1] op_sel_hi:[1,0]
	v_pk_mul_f32 v[14:15], v[14:15], v[0:1] op_sel_hi:[1,0]
	v_pk_mul_f32 v[12:13], v[12:13], v[0:1] op_sel_hi:[1,0]
	v_pk_mul_f32 v[10:11], v[10:11], v[0:1] op_sel_hi:[1,0]
	v_pk_mul_f32 v[8:9], v[8:9], v[0:1] op_sel_hi:[1,0]
	v_pk_mul_f32 v[6:7], v[6:7], v[0:1] op_sel_hi:[1,0]
	v_pk_mul_f32 v[4:5], v[4:5], v[0:1] op_sel_hi:[1,0]
	v_pk_mul_f32 v[2:3], v[2:3], v[0:1] op_sel_hi:[1,0]
.Lattn_fx_skip_790:
	v_cvt_pk_bf16_f32 v158, v176, v177
	v_cvt_pk_bf16_f32 v159, v178, v179
	v_cvt_pk_bf16_f32 v160, v180, v181
	v_cvt_pk_bf16_f32 v161, v182, v183
	v_add_f32_e32 v36, v152, v153
	v_cvt_pk_bf16_f32 v153, v38, v40
	v_cvt_pk_bf16_f32 v152, v34, v37
	s_waitcnt lgkmcnt(0)
	v_mfma_f32_32x32x16_bf16 v[18:33], v[216:219], v[158:161], v[18:33]
	s_add_i32 s8, s8, 32
	v_fmac_f32_e32 v36, v151, v0
	v_add_u32_e32 v150, 64, v150
	v_add_u32_e32 v149, 64, v149
	v_add_u32_e32 v148, 0x1000, v148
	v_mfma_f32_32x32x16_bf16 v[2:17], v[220:223], v[158:161], v[2:17]
	v_cvt_pk_bf16_f32 v154, v42, v44
	v_cvt_pk_bf16_f32 v155, v46, v48
	v_add_u32_e32 v147, 0x1000, v147
	v_add_u32_e32 v91, 0x1000, v91
	v_add_u32_e32 v90, 0x1000, v90
	s_cmpk_eq_i32 s8, 0x100
	v_mfma_f32_32x32x16_bf16 v[18:33], v[224:227], v[152:155], v[18:33]
	v_mfma_f32_32x32x16_bf16 v[2:17], v[228:231], v[152:155], v[2:17]
	s_cbranch_scc1 .Lattn_fx_exit_790_0
	v_mov_b32_e32 v151, v36
	s_branch .LBB0_790
.Lattn_fx_exit_790_0:
	v_mov_b32_e32 v35, v176
	v_mov_b32_e32 v39, v178
	v_mov_b32_e32 v49, v183
	s_branch .LBB0_798

; DI unsigned pack2bf(float a, float b) { const f2_t v = {a, b}; return __builtin_bit_cast(unsigned, __builtin_convertvector(v, bf2_t)); }
; DI float xor32_max(float v) { const auto r = __builtin_amdgcn_permlane32_swap(__float_as_uint(v), __float_as_uint(v), false, false); return fmaxf(__uint_as_float(r[0]), __uint_as_float(r[1])); }
; DI void attn_task(const Params& P, int bh, int n, int t, int lane, const char* Ks, const char* Vs) {
;     ...
; #pragma unroll
;     for (int s = 0; s < 4; ++s) {
;       const bf16x8 kf = *reinterpret_cast<const bf16x8*>(Ks + krow * 128 + (((2 * s + hh) ^ ((krow >> 1) & 7)) * 16));
;       S = __builtin_amdgcn_mfma_f32_32x32x16_bf16(kf, qf[s], S, 0, 0, 0);
;     }
;     const bool diag = own && (kt == t);
;     constexpr float SC2 = 0.125f * 1.4426950408889634f;
;     float mx = -1e30f;
; #pragma unroll
;     for (int i = 0; i < 16; ++i) {
;       if (diag && (kbase + crow(i, hh) > lq)) S[i] = -1e30f;
;       mx = fmaxf(mx, S[i]);
;     }
;     mx = xor32_max(mx);
;     const float m_new = fmaxf(m_run, mx * SC2);
;     const float alpha = __builtin_amdgcn_exp2f(m_run - m_new);
;     float rs = 0.f;
; #pragma unroll
;     for (int i = 0; i < 16; ++i) { float pv = __builtin_amdgcn_exp2f(fmaf(S[i], SC2, -m_new)); S[i] = pv; rs += pv; }
;     rs = xor32_sum(rs);
;     l_run = l_run * alpha + rs; m_run = m_new;
;     if (__ballot(alpha != 1.f)) {
; #pragma unroll
;       for (int i = 0; i < 16; ++i) { O0[i] *= alpha; O1[i] *= alpha; }
;     }
; #pragma unroll
;     for (int s = 0; s < 2; ++s) {
;       const uint4 ppk = make_uint4(pack2bf(S[8 * s], S[8 * s + 1]), pack2bf(S[8 * s + 2], S[8 * s + 3]), pack2bf(S[8 * s + 4], S[8 * s + 5]), pack2bf(S[8 * s + 6], S[8 * s + 7]));
;       const bf16x8 pf = __builtin_bit_cast(bf16x8, ppk);
; #pragma unroll
;       for (int dt = 0; dt < 2; ++dt) {
;         const char* vp = Vs + (dt * 32 + r) * 528 + (kt * 32 + 16 * s + 4 * hh) * 2;
;         const uint2 lo = *reinterpret_cast<const uint2*>(vp), hi = *reinterpret_cast<const uint2*>(vp + 16);
;         const uint4 vv = make_uint4(lo.x, lo.y, hi.x, hi.y);
;         if (dt == 0) O0 = __builtin_amdgcn_mfma_f32_32x32x16_bf16(__builtin_bit_cast(bf16x8, vv), pf, O0, 0, 0, 0);
;         else O1 = __builtin_amdgcn_mfma_f32_32x32x16_bf16(__builtin_bit_cast(bf16x8, vv), pf, O1, 0, 0, 0);
;       }
;     }
.Lattn_fast_815:
	s_waitcnt vmcnt(3) lgkmcnt(2)
	v_mfma_f32_32x32x16_bf16 v[34:49], v[34:37], v[50:53], 0
	s_waitcnt vmcnt(2) lgkmcnt(1)
	v_mfma_f32_32x32x16_bf16 v[34:49], v[154:157], v[54:57], v[34:49]
	ds_read_b128 v[154:157], v153
	v_add_u32_e32 v210, v150, v197
	v_add_u32_e32 v211, v151, v197
	ds_read2_b64 v[216:219], v210 offset1:2
	ds_read2_b64 v[220:223], v211 offset1:2
	ds_read2_b64 v[224:227], v210 offset0:4 offset1:6
	ds_read2_b64 v[228:231], v211 offset0:4 offset1:6
	s_waitcnt vmcnt(1) lgkmcnt(5)
	v_mfma_f32_32x32x16_bf16 v[34:49], v[158:161], v[58:61], v[34:49]
	s_waitcnt vmcnt(0) lgkmcnt(4)
	v_mfma_f32_32x32x16_bf16 v[34:49], v[154:157], v[62:65], v[34:49]
	s_nop 11
	v_max3_f32 v176, v34, s22, v35
	v_max3_f32 v176, v176, v36, v37
	v_max3_f32 v176, v176, v38, v39
	v_max3_f32 v176, v176, v40, v41
	v_max3_f32 v176, v176, v42, v43
	v_max3_f32 v176, v176, v44, v45
	v_max3_f32 v176, v176, v46, v47
	v_max3_f32 v176, v176, v48, v49
	v_mov_b32_e32 v177, v176
	s_nop 1
	v_permlane32_swap_b32_e32 v176, v177
	v_max_f32_e32 v177, v177, v177
	v_max_f32_e32 v176, v176, v176
	v_max_f32_e32 v176, v176, v177
	v_mul_f32_e32 v176, 0x3e38aa3b, v176
	v_max_f32_e32 v177, v0, v0
	v_max_f32_e32 v71, v177, v176
	v_fma_f32 v34, v34, s23, -v71
	v_exp_f32_e32 v176, v34
	v_fma_f32 v34, v35, s23, -v71
	v_exp_f32_e32 v177, v34
	v_fma_f32 v34, v36, s23, -v71
	v_exp_f32_e32 v178, v34
	v_fma_f32 v34, v37, s23, -v71
	v_exp_f32_e32 v179, v34
	v_fma_f32 v35, v38, s23, -v71
	v_add_f32_e32 v34, 0, v176
	v_exp_f32_e32 v180, v35
	v_fma_f32 v35, v39, s23, -v71
	v_add_f32_e32 v34, v177, v34
	v_exp_f32_e32 v181, v35
	v_fma_f32 v35, v40, s23, -v71
	v_add_f32_e32 v34, v178, v34
	v_exp_f32_e32 v182, v35
	v_fma_f32 v35, v41, s23, -v71
	v_add_f32_e32 v34, v179, v34
	v_exp_f32_e32 v183, v35
	v_add_f32_e32 v34, v180, v34
	v_add_f32_e32 v34, v181, v34
	v_add_f32_e32 v34, v182, v34
	v_add_f32_e32 v153, v183, v34
	v_fma_f32 v34, v42, s23, -v71
	v_exp_f32_e32 v34, v34
	v_fma_f32 v35, v43, s23, -v71
	v_exp_f32_e32 v35, v35
	v_fma_f32 v37, v44, s23, -v71
	v_exp_f32_e32 v37, v37
	v_fma_f32 v39, v45, s23, -v71
	v_exp_f32_e32 v39, v39
	v_add_f32_e32 v42, v34, v153
	v_add_f32_e32 v42, v35, v42
	v_add_f32_e32 v42, v37, v42
	v_add_f32_e32 v153, v39, v42
	v_fma_f32 v42, v46, s23, -v71
	v_exp_f32_e32 v42, v42
	v_fma_f32 v43, v47, s23, -v71
	v_exp_f32_e32 v43, v43
	v_fma_f32 v45, v48, s23, -v71
	v_exp_f32_e32 v45, v45
	v_fma_f32 v47, v49, s23, -v71
	v_exp_f32_e32 v47, v47
	v_sub_f32_e32 v0, v0, v71
	v_add_f32_e32 v153, v42, v153
	v_add_f32_e32 v153, v43, v153
	v_exp_f32_e32 v0, v0
	v_add_f32_e32 v153, v45, v153
	v_add_f32_e32 v153, v47, v153
	v_mov_b32_e32 v154, v153
	s_nop 1
	v_permlane32_swap_b32_e32 v153, v154
	v_cmp_neq_f32_e32 vcc, 1.0, v0
	s_cbranch_vccz .Lattn_fx_skip_815
	v_pk_mul_f32 v[32:33], v[32:33], v[0:1] op_sel_hi:[1,0]
	v_pk_mul_f32 v[30:31], v[30:31], v[0:1] op_sel_hi:[1,0]
	v_pk_mul_f32 v[28:29], v[28:29], v[0:1] op_sel_hi:[1,0]
	v_pk_mul_f32 v[26:27], v[26:27], v[0:1] op_sel_hi:[1,0]
	v_pk_mul_f32 v[24:25], v[24:25], v[0:1] op_sel_hi:[1,0]
	v_pk_mul_f32 v[22:23], v[22:23], v[0:1] op_sel_hi:[1,0]
	v_pk_mul_f32 v[20:21], v[20:21], v[0:1] op_sel_hi:[1,0]
	v_pk_mul_f32 v[18:19], v[18:19], v[0:1] op_sel_hi:[1,0]
	v_pk_mul_f32 v[16:17], v[16:17], v[0:1] op_sel_hi:[1,0]
	v_pk_mul_f32 v[14:15], v[14:15], v[0:1] op_sel_hi:[1,0]
	v_pk_mul_f32 v[12:13], v[12:13], v[0:1] op_sel_hi:[1,0]
	v_pk_mul_f32 v[10:11], v[10:11], v[0:1] op_sel_hi:[1,0]
	v_pk_mul_f32 v[8:9], v[8:9], v[0:1] op_sel_hi:[1,0]
	v_pk_mul_f32 v[6:7], v[6:7], v[0:1] op_sel_hi:[1,0]
	v_pk_mul_f32 v[4:5], v[4:5], v[0:1] op_sel_hi:[1,0]
	v_pk_mul_f32 v[2:3], v[2:3], v[0:1] op_sel_hi:[1,0]
.Lattn_fx_skip_815:
	v_cvt_pk_bf16_f32 v164, v176, v177
	v_cvt_pk_bf16_f32 v165, v178, v179
	v_cvt_pk_bf16_f32 v166, v180, v181
	v_cvt_pk_bf16_f32 v167, v182, v183
	v_add_f32_e32 v36, v153, v154
	v_fmac_f32_e32 v36, v152, v0
	s_waitcnt lgkmcnt(0)
	v_mfma_f32_32x32x16_bf16 v[18:33], v[216:219], v[164:167], v[18:33]
	v_cvt_pk_bf16_f32 v39, v37, v39
	v_cvt_pk_bf16_f32 v40, v42, v43
	v_cvt_pk_bf16_f32 v41, v45, v47
	s_add_i32 s8, s8, 32
	v_cmp_eq_u32_e32 vcc, s8, v89
	v_add_u32_e32 v151, 64, v151
	v_add_u32_e32 v150, 64, v150
	v_mfma_f32_32x32x16_bf16 v[2:17], v[220:223], v[164:167], v[2:17]
	v_cvt_pk_bf16_f32 v38, v34, v35
	v_add_u32_e32 v149, 0x1000, v149
	v_add_u32_e32 v148, 0x1000, v148
	v_add_u32_e32 v147, 0x1000, v147
	v_add_u32_e32 v91, 0x1000, v91
	s_or_b64 s[58:59], vcc, s[58:59]
	v_mfma_f32_32x32x16_bf16 v[18:33], v[224:227], v[38:41], v[18:33]
	v_mov_b32_e32 v152, v36
	v_mfma_f32_32x32x16_bf16 v[2:17], v[228:231], v[38:41], v[2:17]
	s_andn2_b64 exec, exec, s[58:59]
	s_cbranch_execz .Lattn_fx_exit_815_0
	s_branch .LBB0_815
.Lattn_fx_exit_815_0:
	v_mov_b32_e32 v49, v183
	s_branch .LBB0_817
